# attention PV block: staging writes later (K after 10th, V after 14th MFMA), dead address adds removed
# baseline (speedup 1.0000x reference)
.LBB0_308:
	v_sub_f32_e32 v0, v160, v215
	v_exp_f32_e32 v0, v0
	v_sub_f32_e32 v160, v161, v215
	v_exp_f32_e32 v160, v160
	v_sub_f32_e32 v161, v162, v215
	v_exp_f32_e32 v161, v161
	v_sub_f32_e32 v162, v163, v215
	v_exp_f32_e32 v162, v162
	v_sub_f32_e32 v164, v164, v215
	v_add_f32_e32 v163, v207, v0
	v_exp_f32_e32 v164, v164
	v_add_f32_e32 v163, v160, v163
	v_add_f32_e32 v163, v161, v163
	v_sub_f32_e32 v165, v165, v215
	v_add_f32_e32 v163, v162, v163
	v_exp_f32_e32 v165, v165
	v_sub_f32_e32 v166, v166, v215
	v_exp_f32_e32 v166, v166
	v_sub_f32_e32 v167, v167, v215
	v_add_f32_e32 v163, v164, v163
	v_cvt_pk_bf16_f32 v160, v0, v160
	v_cvt_pk_bf16_f32 v161, v161, v162
	v_cvt_pk_bf16_f32 v162, v164, v165
	v_sub_f32_e32 v164, v169, v215
	v_exp_f32_e32 v167, v167
	v_sub_f32_e32 v0, v168, v215
	v_exp_f32_e32 v168, v164
	v_sub_f32_e32 v164, v170, v215
	v_exp_f32_e32 v169, v164
	v_sub_f32_e32 v164, v171, v215
	v_add_f32_e32 v163, v165, v163
	v_exp_f32_e32 v170, v164
	v_sub_f32_e32 v164, v172, v215
	v_add_f32_e32 v163, v166, v163
	v_exp_f32_e32 v171, v164
	v_sub_f32_e32 v164, v173, v215
	v_sub_f32_e32 v14, v14, v215
	v_sub_f32_e32 v15, v15, v215
	v_add_f32_e32 v175, v167, v163
	v_cvt_pk_bf16_f32 v163, v166, v167
	v_exp_f32_e32 v0, v0
	v_exp_f32_e32 v172, v164
	v_exp_f32_e32 v14, v14
	v_exp_f32_e32 v15, v15
	v_cvt_pk_bf16_f32 v164, v0, v168
	v_cvt_pk_bf16_f32 v165, v169, v170
	v_cvt_pk_bf16_f32 v166, v171, v172
	v_cvt_pk_bf16_f32 v167, v14, v15
	s_waitcnt lgkmcnt(3)
	v_mfma_f32_32x32x16_bf16 v[128:143], v[148:151], v[160:163], v[128:143]
	s_waitcnt lgkmcnt(1)
	v_mfma_f32_32x32x16_bf16 v[112:127], v[156:159], v[160:163], v[112:127]
	v_mfma_f32_32x32x16_bf16 v[128:143], v[144:147], v[164:167], v[128:143]
	ds_read_b128 v[144:147], v174 offset:25120
	s_waitcnt lgkmcnt(1)
	v_mfma_f32_32x32x16_bf16 v[112:127], v[152:155], v[164:167], v[112:127]
	ds_read_b128 v[148:151], v174 offset:22528
	ds_read_b128 v[152:155], v174 offset:22560
	ds_read_b128 v[156:159], v174 offset:25088
	s_waitcnt lgkmcnt(2)
	v_mfma_f32_32x32x16_bf16 v[96:111], v[148:151], v[160:163], v[96:111]
	s_waitcnt lgkmcnt(0)
	v_mfma_f32_32x32x16_bf16 v[80:95], v[156:159], v[160:163], v[80:95]
	v_mfma_f32_32x32x16_bf16 v[96:111], v[152:155], v[164:167], v[96:111]
	v_mfma_f32_32x32x16_bf16 v[80:95], v[144:147], v[164:167], v[80:95]
	ds_read_b128 v[144:147], v174 offset:30240
	ds_read_b128 v[148:151], v174 offset:27648
	ds_read_b128 v[152:155], v174 offset:27680
	ds_read_b128 v[156:159], v174 offset:30208
	s_waitcnt lgkmcnt(2)
	v_mfma_f32_32x32x16_bf16 v[64:79], v[148:151], v[160:163], v[64:79]
	s_waitcnt lgkmcnt(0)
	v_mfma_f32_32x32x16_bf16 v[48:63], v[156:159], v[160:163], v[48:63]
	v_subrev_u32_e32 v250, s73, v213
	s_waitcnt vmcnt(2)
	ds_write_b128 v250, v[2:5] offset:37888
	ds_write_b128 v250, v[6:9] offset:46592
	v_mfma_f32_32x32x16_bf16 v[64:79], v[152:155], v[164:167], v[64:79]
	v_mfma_f32_32x32x16_bf16 v[48:63], v[144:147], v[164:167], v[48:63]
	ds_read_b128 v[144:147], v174 offset:35360
	ds_read_b128 v[148:151], v174 offset:32768
	ds_read_b128 v[152:155], v174 offset:32800
	ds_read_b128 v[156:159], v174 offset:35328
	s_waitcnt lgkmcnt(2)
	v_mfma_f32_32x32x16_bf16 v[32:47], v[148:151], v[160:163], v[32:47]
	s_waitcnt lgkmcnt(0)
	v_mfma_f32_32x32x16_bf16 v[16:31], v[156:159], v[160:163], v[16:31]
	v_subrev_u32_e32 v250, s73, v214
	v_add_u32_e32 v2, 0xd800, v250
	v_add_u32_e32 v250, 0x10000, v250
	s_waitcnt vmcnt(0)
	ds_write2_b64 v2, v[10:11], v[12:13] offset1:2
	ds_write2_b64 v250, v[176:177], v[178:179] offset1:2
	v_mfma_f32_32x32x16_bf16 v[32:47], v[152:155], v[164:167], v[32:47]
	v_mfma_f32_32x32x16_bf16 v[16:31], v[144:147], v[164:167], v[16:31]
	v_add_f32_e32 v0, v0, v175
	v_add_f32_e32 v0, v168, v0
	v_add_f32_e32 v0, v169, v0
	v_add_f32_e32 v0, v170, v0
	v_add_f32_e32 v0, v171, v0
	v_add_f32_e32 v0, v172, v0
	v_add_f32_e32 v0, v14, v0
	v_add_f32_e32 v207, v15, v0
	s_add_i32 s77, s77, 1
	v_lshl_add_u64 v[188:189], v[188:189], 0, 64
	s_mov_b64 vcc, 0x80000
	s_cmp_eq_u32 s79, s77
	v_lshl_add_u64 v[190:191], v[190:191], 0, vcc
	s_branch .Lat_step_end

.Lat_nostag:
	v_lshl_add_u64 v[2:3], s[30:31], 0, v[190:191]
	s_mov_b32 s73, 0x13481000
	v_add_co_u32_e32 v6, vcc, s73, v2
	v_lshl_add_u64 v[10:11], s[30:31], 0, v[188:189]
	s_nop 0
	v_addc_co_u32_e32 v7, vcc, 0, v3, vcc
	v_add_co_u32_e32 v12, vcc, 0x1f400000, v10
	global_load_dwordx4 v[2:5], v[6:7], off
	s_nop 0
	global_load_dwordx4 v[6:9], v[6:7], off offset:256
	v_addc_co_u32_e32 v13, vcc, 0, v11, vcc
	v_add_co_u32_e32 v14, vcc, 0x1f480000, v10
	s_bitcmp1_b32 s77, 0
	s_nop 0
	v_addc_co_u32_e32 v15, vcc, 0, v11, vcc
	global_load_dwordx4 v[10:13], v[12:13], off offset:64
	s_nop 0
	global_load_dwordx4 v[176:179], v[14:15], off offset:64
	s_cselect_b32 s73, 0x9400, 0
	s_cmp_gt_u32 s77, s49
	s_cbranch_scc1 .LBB0_309
	s_add_i32 vcc_lo, s73, 0
	s_add_i32 vcc_hi, vcc_lo, s78
	v_add3_u32 v0, vcc_hi, v211, v209
	v_add_u32_e32 v14, v210, v209
	ds_read_b128 v[144:147], v0
	ds_read_b128 v[160:163], v0 offset:32
	ds_read_b128 v[148:151], v14
	ds_read_b128 v[164:167], v14 offset:32
	ds_read_b128 v[216:219], v0 offset:64
	ds_read_b128 v[220:223], v0 offset:96
	ds_read_b128 v[224:227], v14 offset:64
	ds_read_b128 v[228:231], v14 offset:96
	v_add_u32_e32 v250, vcc_lo, v212
	s_waitcnt lgkmcnt(5)
	v_mfma_f32_32x32x16_bf16 v[144:159], v[144:147], v[148:151], 0
	s_waitcnt lgkmcnt(4)
	v_mfma_f32_32x32x16_bf16 v[160:175], v[160:163], v[164:167], 0
	s_waitcnt lgkmcnt(1)
	v_mfma_f32_32x32x16_bf16 v[144:159], v[216:219], v[224:227], v[144:159]
	ds_read_b128 v[216:219], v0 offset:128
	ds_read_b128 v[224:227], v0 offset:160
	ds_read_b128 v[232:235], v14 offset:128
	ds_read_b128 v[236:239], v14 offset:160
	ds_read_b128 v[240:243], v0 offset:192
	ds_read_b128 v[244:247], v0 offset:224
	ds_read_b128 v[180:183], v14 offset:192
	ds_read_b128 v[184:187], v14 offset:224
	s_waitcnt lgkmcnt(8)
	v_mfma_f32_32x32x16_bf16 v[160:175], v[220:223], v[228:231], v[160:175]
	s_waitcnt lgkmcnt(5)
	v_mfma_f32_32x32x16_bf16 v[144:159], v[216:219], v[232:235], v[144:159]
	s_waitcnt lgkmcnt(4)
	v_mfma_f32_32x32x16_bf16 v[160:175], v[224:227], v[236:239], v[160:175]
	s_waitcnt lgkmcnt(1)
	v_mfma_f32_32x32x16_bf16 v[144:159], v[240:243], v[180:183], v[144:159]
	s_waitcnt lgkmcnt(0)
	v_mfma_f32_32x32x16_bf16 v[160:175], v[244:247], v[184:187], v[160:175]
	s_nop 11
	v_pk_add_f32 v[14:15], v[158:159], v[174:175]
	v_add_u32_e32 v174, v250, v208
	v_pk_add_f32 v[166:167], v[150:151], v[166:167]
	v_pk_add_f32 v[164:165], v[148:149], v[164:165]
	v_pk_add_f32 v[162:163], v[146:147], v[162:163]
	v_pk_add_f32 v[160:161], v[144:145], v[160:161]
	ds_read_b128 v[148:151], v174 offset:17408
	ds_read_b128 v[144:147], v174 offset:17440
	v_pk_add_f32 v[172:173], v[156:157], v[172:173]
	v_pk_add_f32 v[170:171], v[154:155], v[170:171]
	v_pk_add_f32 v[168:169], v[152:153], v[168:169]
	ds_read_b128 v[156:159], v174 offset:19968
	ds_read_b128 v[152:155], v174 offset:20000
	s_cmp_lg_u32 s49, s77
	s_cbranch_scc1 .LBB0_313
	v_cndmask_b32_e64 v0, v160, v202, s[90:91]
	v_cndmask_b32_e64 v161, v202, v161, s[88:89]
	v_cndmask_b32_e64 v160, v0, v160, s[88:89]
	v_cndmask_b32_e64 v162, v162, v202, s[92:93]
	v_cndmask_b32_e64 v163, v163, v202, s[94:95]
	v_cndmask_b32_e64 v164, v164, v202, s[96:97]
	v_cndmask_b32_e64 v165, v165, v202, s[4:5]
	v_cndmask_b32_e64 v166, v166, v202, s[6:7]
	v_cndmask_b32_e64 v167, v167, v202, s[8:9]
	v_cndmask_b32_e64 v168, v168, v202, s[10:11]
	v_cndmask_b32_e64 v169, v169, v202, s[12:13]
	v_cndmask_b32_e64 v170, v170, v202, s[14:15]
	v_cndmask_b32_e64 v171, v171, v202, s[16:17]
	v_cndmask_b32_e64 v172, v172, v202, s[18:19]
	v_cndmask_b32_e64 v173, v173, v202, s[20:21]
	v_cndmask_b32_e64 v14, v14, v202, s[22:23]
	v_cndmask_b32_e64 v15, v15, v202, s[24:25]

.LBB0_315:
	s_or_b32 s28, s28, 2
	s_cmp_ge_u32 s28, s49
	s_cbranch_scc1 .LBB0_321
	s_bitcmp1_b32 s79, 0
	s_cselect_b32 s28, 0x9400, 0
	s_add_i32 s28, s28, 0
	s_add_i32 s73, s28, s78
	v_add3_u32 v0, s73, v211, v209
	v_add_u32_e32 v180, s28, v212
	v_add_u32_e32 v14, v210, v209
	ds_read_b128 v[2:5], v0
	ds_read_b128 v[6:9], v0 offset:32
	ds_read_b128 v[10:13], v14
	ds_read_b128 v[160:163], v14 offset:32
	ds_read_b128 v[176:179], v0 offset:64
	ds_read_b128 v[188:191], v14 offset:64
	ds_read_b128 v[210:213], v0 offset:96
	ds_read_b128 v[216:219], v14 offset:96
	s_waitcnt lgkmcnt(5)
	v_mfma_f32_32x32x16_bf16 v[144:159], v[2:5], v[10:13], 0
	s_waitcnt lgkmcnt(4)
	v_mfma_f32_32x32x16_bf16 v[160:175], v[6:9], v[160:163], 0
	s_waitcnt lgkmcnt(2)
	v_mfma_f32_32x32x16_bf16 v[144:159], v[176:179], v[188:191], v[144:159]
	ds_read_b128 v[2:5], v0 offset:128
	ds_read_b128 v[6:9], v0 offset:160
	ds_read_b128 v[10:13], v14 offset:128
	ds_read_b128 v[176:179], v14 offset:160
	ds_read_b128 v[188:191], v0 offset:192
	ds_read_b128 v[220:223], v0 offset:224
	ds_read_b128 v[224:227], v14 offset:192
	ds_read_b128 v[228:231], v14 offset:224
	s_waitcnt lgkmcnt(8)
	v_mfma_f32_32x32x16_bf16 v[160:175], v[210:213], v[216:219], v[160:175]
	s_waitcnt lgkmcnt(5)
	v_mfma_f32_32x32x16_bf16 v[144:159], v[2:5], v[10:13], v[144:159]
	s_waitcnt lgkmcnt(4)
	v_mfma_f32_32x32x16_bf16 v[160:175], v[6:9], v[176:179], v[160:175]
	s_waitcnt lgkmcnt(1)
	v_mfma_f32_32x32x16_bf16 v[144:159], v[188:191], v[224:227], v[144:159]
	s_waitcnt lgkmcnt(0)
	v_mfma_f32_32x32x16_bf16 v[160:175], v[220:223], v[228:231], v[160:175]
	s_nop 11
	v_pk_add_f32 v[14:15], v[158:159], v[174:175]
	v_pk_add_f32 v[158:159], v[146:147], v[162:163]
	v_add_u32_e32 v162, v180, v208
	ds_read_b128 v[6:9], v162 offset:17408
	ds_read_b128 v[2:5], v162 offset:17440
	v_pk_add_f32 v[160:161], v[144:145], v[160:161]
	ds_read_b128 v[144:147], v162 offset:19968
	ds_read_b128 v[10:13], v162 offset:20000
	v_pk_add_f32 v[156:157], v[156:157], v[172:173]
	v_pk_add_f32 v[154:155], v[154:155], v[170:171]
	v_pk_add_f32 v[152:153], v[152:153], v[168:169]
	v_pk_add_f32 v[150:151], v[150:151], v[166:167]
	v_pk_add_f32 v[148:149], v[148:149], v[164:165]
	s_cmp_lg_u32 s79, s49
	s_cbranch_scc1 .LBB0_318
	v_cndmask_b32_e64 v0, v160, v202, s[90:91]
	v_cndmask_b32_e64 v161, v202, v161, s[88:89]
	v_cndmask_b32_e64 v160, v0, v160, s[88:89]
	v_cndmask_b32_e64 v158, v158, v202, s[92:93]
	v_cndmask_b32_e64 v159, v159, v202, s[94:95]
	v_cndmask_b32_e64 v148, v148, v202, s[96:97]
	v_cndmask_b32_e64 v149, v149, v202, s[4:5]
	v_cndmask_b32_e64 v150, v150, v202, s[6:7]
	v_cndmask_b32_e64 v151, v151, v202, s[8:9]
	v_cndmask_b32_e64 v152, v152, v202, s[10:11]
	v_cndmask_b32_e64 v153, v153, v202, s[12:13]
	v_cndmask_b32_e64 v154, v154, v202, s[14:15]
	v_cndmask_b32_e64 v155, v155, v202, s[16:17]
	v_cndmask_b32_e64 v156, v156, v202, s[18:19]
	v_cndmask_b32_e64 v157, v157, v202, s[20:21]
	v_cndmask_b32_e64 v14, v14, v202, s[22:23]
	v_cndmask_b32_e64 v15, v15, v202, s[24:25]

.LBB0_320:
	v_sub_f32_e32 v0, v160, v215
	v_exp_f32_e32 v0, v0
	v_sub_f32_e32 v160, v161, v215
	v_exp_f32_e32 v160, v160
	v_sub_f32_e32 v158, v158, v215
	v_exp_f32_e32 v158, v158
	v_sub_f32_e32 v159, v159, v215
	v_exp_f32_e32 v159, v159
	v_sub_f32_e32 v148, v148, v215
	v_add_f32_e32 v161, v207, v0
	v_exp_f32_e32 v163, v148
	v_sub_f32_e32 v148, v149, v215
	v_add_f32_e32 v161, v160, v161
	v_exp_f32_e32 v164, v148
	v_sub_f32_e32 v148, v150, v215
	v_add_f32_e32 v161, v158, v161
	v_exp_f32_e32 v165, v148
	v_sub_f32_e32 v148, v151, v215
	v_add_f32_e32 v161, v159, v161
	v_exp_f32_e32 v151, v148
	v_add_f32_e32 v148, v163, v161
	v_add_f32_e32 v148, v164, v148
	v_add_f32_e32 v148, v165, v148
	v_add_f32_e32 v161, v151, v148
	v_cvt_pk_bf16_f32 v148, v0, v160
	v_sub_f32_e32 v0, v152, v215
	v_sub_f32_e32 v152, v153, v215
	v_cvt_pk_bf16_f32 v149, v158, v159
	v_exp_f32_e32 v158, v152
	v_sub_f32_e32 v152, v154, v215
	v_exp_f32_e32 v159, v152
	v_sub_f32_e32 v152, v155, v215
	v_exp_f32_e32 v160, v152
	v_sub_f32_e32 v152, v156, v215
	v_exp_f32_e32 v156, v152
	v_sub_f32_e32 v152, v157, v215
	v_sub_f32_e32 v14, v14, v215
	v_sub_f32_e32 v15, v15, v215
	v_cvt_pk_bf16_f32 v150, v163, v164
	v_cvt_pk_bf16_f32 v151, v165, v151
	v_exp_f32_e32 v0, v0
	v_exp_f32_e32 v157, v152
	v_exp_f32_e32 v14, v14
	v_exp_f32_e32 v15, v15
	v_cvt_pk_bf16_f32 v152, v0, v158
	v_cvt_pk_bf16_f32 v153, v159, v160
	v_cvt_pk_bf16_f32 v154, v156, v157
	v_cvt_pk_bf16_f32 v155, v14, v15
	s_waitcnt lgkmcnt(3)
	v_mfma_f32_32x32x16_bf16 v[128:143], v[6:9], v[148:151], v[128:143]
	s_waitcnt lgkmcnt(1)
	v_mfma_f32_32x32x16_bf16 v[112:127], v[144:147], v[148:151], v[112:127]
	v_mfma_f32_32x32x16_bf16 v[128:143], v[2:5], v[152:155], v[128:143]
	ds_read_b128 v[2:5], v162 offset:25120
	s_waitcnt lgkmcnt(1)
	v_mfma_f32_32x32x16_bf16 v[112:127], v[10:13], v[152:155], v[112:127]
	ds_read_b128 v[6:9], v162 offset:22528
	ds_read_b128 v[10:13], v162 offset:22560
	ds_read_b128 v[144:147], v162 offset:25088
	s_waitcnt lgkmcnt(2)
	v_mfma_f32_32x32x16_bf16 v[96:111], v[6:9], v[148:151], v[96:111]
	s_waitcnt lgkmcnt(0)
	v_mfma_f32_32x32x16_bf16 v[80:95], v[144:147], v[148:151], v[80:95]
	v_mfma_f32_32x32x16_bf16 v[96:111], v[10:13], v[152:155], v[96:111]
	v_mfma_f32_32x32x16_bf16 v[80:95], v[2:5], v[152:155], v[80:95]
	ds_read_b128 v[2:5], v162 offset:30240
	ds_read_b128 v[6:9], v162 offset:27648
	ds_read_b128 v[10:13], v162 offset:27680
	ds_read_b128 v[144:147], v162 offset:30208
	s_waitcnt lgkmcnt(2)
	v_mfma_f32_32x32x16_bf16 v[64:79], v[6:9], v[148:151], v[64:79]
	s_waitcnt lgkmcnt(0)
	v_mfma_f32_32x32x16_bf16 v[48:63], v[144:147], v[148:151], v[48:63]
	v_mfma_f32_32x32x16_bf16 v[64:79], v[10:13], v[152:155], v[64:79]
	v_mfma_f32_32x32x16_bf16 v[48:63], v[2:5], v[152:155], v[48:63]
	ds_read_b128 v[2:5], v162 offset:35360
	ds_read_b128 v[6:9], v162 offset:32768
	ds_read_b128 v[10:13], v162 offset:32800
	ds_read_b128 v[144:147], v162 offset:35328
	s_waitcnt lgkmcnt(2)
	v_mfma_f32_32x32x16_bf16 v[32:47], v[6:9], v[148:151], v[32:47]
	s_waitcnt lgkmcnt(0)
	v_mfma_f32_32x32x16_bf16 v[16:31], v[144:147], v[148:151], v[16:31]
	v_mfma_f32_32x32x16_bf16 v[32:47], v[10:13], v[152:155], v[32:47]
	v_mfma_f32_32x32x16_bf16 v[16:31], v[2:5], v[152:155], v[16:31]
	v_add_f32_e32 v0, v0, v161
	v_add_f32_e32 v0, v158, v0
	v_add_f32_e32 v0, v159, v0
	v_add_f32_e32 v0, v160, v0
	v_add_f32_e32 v0, v156, v0
	v_add_f32_e32 v0, v157, v0
	v_add_f32_e32 v0, v14, v0
	v_add_f32_e32 v207, v15, v0
